# NSA compressed pass 2: V fragment LDS reads of the PV step issued together
# baseline (speedup 1.0000x reference)
.LBB0_1076:
	s_add_i32 s10, s40, 0
	v_add_u32_e32 v87, s10, v163
	v_add_u32_e32 v86, s10, v211
	v_add_u32_e32 v88, s10, v165
	v_add_u32_e32 v89, s10, v212
	ds_read_b128 v[116:119], v87
	ds_read_b128 v[120:123], v86
	ds_read_b128 v[124:127], v88
	ds_read_b128 v[128:131], v89
	ds_read_b128 v[132:135], v87 offset:4096
	ds_read_b128 v[136:139], v86 offset:4096
	ds_read_b128 v[140:143], v88 offset:4096
	ds_read_b128 v[224:227], v89 offset:4096
	s_waitcnt lgkmcnt(6)
	v_mfma_f32_16x16x32_bf16 v[90:93], v[116:119], v[14:17], 0
	v_mfma_f32_16x16x32_bf16 v[90:93], v[120:123], v[2:5], v[90:93]
	s_waitcnt lgkmcnt(4)
	v_mfma_f32_16x16x32_bf16 v[58:61], v[124:127], v[14:17], 0
	v_mfma_f32_16x16x32_bf16 v[58:61], v[128:131], v[2:5], v[58:61]
	s_waitcnt lgkmcnt(2)
	v_mfma_f32_16x16x32_bf16 v[54:57], v[132:135], v[14:17], 0
	v_mfma_f32_16x16x32_bf16 v[54:57], v[136:139], v[2:5], v[54:57]
	s_waitcnt lgkmcnt(0)
	v_mfma_f32_16x16x32_bf16 v[50:53], v[140:143], v[14:17], 0
	v_mfma_f32_16x16x32_bf16 v[50:53], v[224:227], v[2:5], v[50:53]
	v_cmp_lt_i32_e32 vcc, 0, v84
	s_nop 0
	v_sub_f32_e32 v90, v90, v81
	v_sub_f32_e32 v91, v91, v81
	v_exp_f32_e32 v90, v90
	v_exp_f32_e32 v91, v91
	v_sub_f32_e32 v92, v92, v81
	v_sub_f32_e32 v93, v93, v81
	v_exp_f32_e32 v92, v92
	v_exp_f32_e32 v93, v93
	v_mul_f32_e64 v94, v66, v90
	v_mul_f32_e64 v95, v67, v91
	v_cndmask_b32_e32 v90, 0, v95, vcc
	v_cmp_lt_i32_e32 vcc, -1, v84
	s_nop 1
	v_cndmask_b32_e32 v91, 0, v94, vcc
	v_add_f32_e32 v94, 0, v91
	v_add_f32_e32 v96, v90, v94
	v_pk_mul_f32 v[94:95], v[66:67], v[92:93]
	v_cmp_lt_i32_e32 vcc, 2, v84
	s_nop 1
	v_cndmask_b32_e32 v92, 0, v95, vcc
	v_cmp_lt_i32_e32 vcc, 1, v84
	s_nop 1
	v_cndmask_b32_e32 v93, 0, v94, vcc
	v_add_f32_e32 v94, v93, v96
	v_add_f32_e32 v94, v92, v94
	s_nop 1
	v_add_f32_dpp v94, v94, v94 quad_perm:[1,0,3,2] row_mask:0xf bank_mask:0xf bound_ctrl:1
	s_nop 1
	v_mov_b32_dpp v95, v94 quad_perm:[2,3,0,1] row_mask:0xf bank_mask:0xf bound_ctrl:1
	s_and_saveexec_b64 s[6:7], s[30:31]
	v_add_f32_e32 v94, v94, v95
	ds_write_b32 v0, v94
	s_or_b64 exec, exec, s[6:7]
	v_sub_f32_e32 v58, v58, v81
	v_sub_f32_e32 v59, v59, v81
	v_exp_f32_e32 v58, v58
	v_exp_f32_e32 v59, v59
	v_cmp_lt_i32_e32 vcc, 4, v84
	v_pk_mul_f32 v[94:95], v[66:67], v[58:59]
	v_sub_f32_e32 v59, v60, v81
	v_exp_f32_e32 v60, v59
	v_sub_f32_e32 v59, v61, v81
	v_exp_f32_e32 v61, v59
	v_cndmask_b32_e32 v58, 0, v95, vcc
	v_cmp_lt_i32_e32 vcc, 3, v84
	s_nop 1
	v_cndmask_b32_e32 v59, 0, v94, vcc
	v_add_f32_e32 v94, 0, v59
	v_add_f32_e32 v96, v58, v94
	v_pk_mul_f32 v[94:95], v[66:67], v[60:61]
	v_cmp_lt_i32_e32 vcc, 6, v84
	s_nop 1
	v_cndmask_b32_e32 v60, 0, v95, vcc
	v_cmp_lt_i32_e32 vcc, 5, v84
	s_nop 1
	v_cndmask_b32_e32 v61, 0, v94, vcc
	v_add_f32_e32 v94, v61, v96
	v_add_f32_e32 v94, v60, v94
	s_nop 1
	v_add_f32_dpp v94, v94, v94 quad_perm:[1,0,3,2] row_mask:0xf bank_mask:0xf bound_ctrl:1
	s_nop 1
	v_mov_b32_dpp v95, v94 quad_perm:[2,3,0,1] row_mask:0xf bank_mask:0xf bound_ctrl:1
	s_and_saveexec_b64 s[6:7], s[30:31]
	v_add_f32_e32 v94, v94, v95
	ds_write_b32 v0, v94 offset:4
	s_or_b64 exec, exec, s[6:7]
	v_sub_f32_e32 v54, v54, v81
	v_sub_f32_e32 v55, v55, v81
	v_exp_f32_e32 v54, v54
	v_exp_f32_e32 v55, v55
	v_cmp_lt_i32_e32 vcc, 32, v84
	v_pk_mul_f32 v[94:95], v[66:67], v[54:55]
	v_sub_f32_e32 v55, v56, v81
	v_exp_f32_e32 v56, v55
	v_sub_f32_e32 v55, v57, v81
	v_exp_f32_e32 v57, v55
	v_cndmask_b32_e32 v54, 0, v95, vcc
	v_cmp_lt_i32_e32 vcc, 31, v84
	s_nop 1
	v_cndmask_b32_e32 v55, 0, v94, vcc
	v_add_f32_e32 v94, 0, v55
	v_add_f32_e32 v96, v54, v94
	v_pk_mul_f32 v[94:95], v[66:67], v[56:57]
	v_cmp_lt_i32_e32 vcc, 34, v84
	s_nop 1
	v_cndmask_b32_e32 v56, 0, v95, vcc
	v_cmp_lt_i32_e32 vcc, 33, v84
	s_nop 1
	v_cndmask_b32_e32 v57, 0, v94, vcc
	v_add_f32_e32 v94, v57, v96
	v_add_f32_e32 v94, v56, v94
	s_nop 1
	v_add_f32_dpp v94, v94, v94 quad_perm:[1,0,3,2] row_mask:0xf bank_mask:0xf bound_ctrl:1
	s_nop 1
	v_mov_b32_dpp v95, v94 quad_perm:[2,3,0,1] row_mask:0xf bank_mask:0xf bound_ctrl:1
	s_and_saveexec_b64 s[6:7], s[30:31]
	v_add_f32_e32 v94, v94, v95
	ds_write_b32 v0, v94 offset:32
	s_or_b64 exec, exec, s[6:7]
	v_sub_f32_e32 v50, v50, v81
	v_sub_f32_e32 v51, v51, v81
	v_exp_f32_e32 v50, v50
	v_exp_f32_e32 v51, v51
	v_cmp_lt_i32_e32 vcc, 36, v84
	v_pk_mul_f32 v[94:95], v[66:67], v[50:51]
	v_sub_f32_e32 v51, v52, v81
	v_exp_f32_e32 v52, v51
	v_sub_f32_e32 v51, v53, v81
	v_exp_f32_e32 v53, v51
	v_cndmask_b32_e32 v50, 0, v95, vcc
	v_cmp_lt_i32_e32 vcc, 35, v84
	s_nop 1
	v_cndmask_b32_e32 v51, 0, v94, vcc
	v_add_f32_e32 v94, 0, v51
	v_add_f32_e32 v96, v50, v94
	v_pk_mul_f32 v[94:95], v[66:67], v[52:53]
	v_cmp_lt_i32_e32 vcc, 38, v84
	s_nop 1
	v_cndmask_b32_e32 v52, 0, v95, vcc
	v_cmp_lt_i32_e32 vcc, 37, v84
	s_nop 1
	v_cndmask_b32_e32 v53, 0, v94, vcc
	v_add_f32_e32 v94, v53, v96
	v_add_f32_e32 v94, v52, v94
	s_nop 1
	v_add_f32_dpp v94, v94, v94 quad_perm:[1,0,3,2] row_mask:0xf bank_mask:0xf bound_ctrl:1
	s_nop 1
	v_mov_b32_dpp v95, v94 quad_perm:[2,3,0,1] row_mask:0xf bank_mask:0xf bound_ctrl:1
	s_and_saveexec_b64 s[6:7], s[30:31]
	v_add_f32_e32 v94, v94, v95
	ds_write_b32 v0, v94 offset:36
	s_or_b64 exec, exec, s[6:7]
	v_cvt_pk_bf16_f32 v94, v91, v90
	v_add_u32_e32 v90, s10, v215
	v_cvt_pk_bf16_f32 v96, v59, v58
	v_cvt_pk_bf16_f32 v97, v61, v60
	ds_read_b128 v[98:101], v90 offset:8192
	ds_read_b128 v[106:109], v90 offset:10240
	ds_read_b128 v[228:231], v90 offset:12288
	ds_read_b128 v[236:239], v90 offset:14336
	s_waitcnt lgkmcnt(4)
	v_add_u32_e32 v91, s10, v216
	ds_read_b128 v[102:105], v91 offset:8192
	ds_read_b128 v[110:113], v91 offset:10240
	ds_read_b128 v[232:235], v91 offset:12288
	ds_read_b128 v[240:243], v91 offset:14336
	v_cvt_pk_bf16_f32 v54, v55, v54
	v_cvt_pk_bf16_f32 v55, v57, v56
	v_cvt_pk_bf16_f32 v56, v51, v50
	v_cvt_pk_bf16_f32 v57, v53, v52
	s_nop 0
	v_cvt_pk_bf16_f32 v95, v93, v92
	v_cmp_lt_i32_e32 vcc, 0, v83
	s_nop 0
	s_waitcnt lgkmcnt(7)
	v_mfma_f32_16x16x32_bf16 v[46:49], v[98:101], v[94:97], v[46:49]
	s_nop 0
	s_nop 0
	s_waitcnt lgkmcnt(3)
	v_mfma_f32_16x16x32_bf16 v[46:49], v[102:105], v[54:57], v[46:49]
	s_nop 0
	s_nop 0
	v_mfma_f32_16x16x32_bf16 v[34:37], v[106:109], v[94:97], v[34:37]
	s_nop 0
	s_nop 0
	s_waitcnt lgkmcnt(2)
	v_mfma_f32_16x16x32_bf16 v[34:37], v[110:113], v[54:57], v[34:37]
	s_nop 0
	s_nop 0
	v_mfma_f32_16x16x32_bf16 v[42:45], v[228:231], v[94:97], v[42:45]
	s_nop 0
	s_nop 0
	s_waitcnt lgkmcnt(1)
	v_mfma_f32_16x16x32_bf16 v[42:45], v[232:235], v[54:57], v[42:45]
	s_nop 0
	s_nop 0
	v_mfma_f32_16x16x32_bf16 v[38:41], v[236:239], v[94:97], v[38:41]
	s_nop 0
	s_waitcnt lgkmcnt(0)
	v_mfma_f32_16x16x32_bf16 v[38:41], v[240:243], v[54:57], v[38:41]
	v_mfma_f32_16x16x32_bf16 v[92:95], v[116:119], v[10:13], 0
	v_mfma_f32_16x16x32_bf16 v[92:95], v[120:123], v[6:9], v[92:95]
	v_mfma_f32_16x16x32_bf16 v[58:61], v[124:127], v[10:13], 0
	v_mfma_f32_16x16x32_bf16 v[58:61], v[128:131], v[6:9], v[58:61]
	v_mfma_f32_16x16x32_bf16 v[54:57], v[132:135], v[10:13], 0
	v_mfma_f32_16x16x32_bf16 v[54:57], v[136:139], v[6:9], v[54:57]
	v_mfma_f32_16x16x32_bf16 v[50:53], v[140:143], v[10:13], 0
	v_mfma_f32_16x16x32_bf16 v[50:53], v[224:227], v[6:9], v[50:53]
	s_nop 1
	v_sub_f32_e32 v86, v92, v82
	v_sub_f32_e32 v87, v93, v82
	v_exp_f32_e32 v86, v86
	v_exp_f32_e32 v87, v87
	s_nop 0
	v_pk_mul_f32 v[88:89], v[68:69], v[86:87]
	s_nop 0
	v_cndmask_b32_e32 v86, 0, v89, vcc
	v_cmp_lt_i32_e32 vcc, -1, v83
	v_sub_f32_e32 v89, v95, v82
	v_exp_f32_e32 v89, v89
	v_cndmask_b32_e32 v87, 0, v88, vcc
	v_add_f32_e32 v88, 0, v87
	v_add_f32_e32 v96, v86, v88
	v_sub_f32_e32 v88, v94, v82
	v_exp_f32_e32 v88, v88
	v_cmp_lt_i32_e32 vcc, 2, v83
	v_pk_mul_f32 v[92:93], v[68:69], v[88:89]
	s_nop 0
	v_cndmask_b32_e32 v88, 0, v93, vcc
	v_cmp_lt_i32_e32 vcc, 1, v83
	s_nop 1
	v_cndmask_b32_e32 v89, 0, v92, vcc
	v_add_f32_e32 v92, v89, v96
	v_add_f32_e32 v92, v88, v92
	s_nop 1
	v_add_f32_dpp v92, v92, v92 quad_perm:[1,0,3,2] row_mask:0xf bank_mask:0xf bound_ctrl:1
	s_nop 1
	v_mov_b32_dpp v93, v92 quad_perm:[2,3,0,1] row_mask:0xf bank_mask:0xf bound_ctrl:1
	s_and_saveexec_b64 s[6:7], s[30:31]
	v_add_f32_e32 v92, v92, v93
	ds_write_b32 v0, v92 offset:4096
	s_or_b64 exec, exec, s[6:7]
	v_sub_f32_e32 v58, v58, v82
	v_sub_f32_e32 v59, v59, v82
	v_exp_f32_e32 v58, v58
	v_exp_f32_e32 v59, v59
	v_cmp_lt_i32_e32 vcc, 4, v83
	v_pk_mul_f32 v[92:93], v[68:69], v[58:59]
	v_sub_f32_e32 v59, v60, v82
	v_exp_f32_e32 v60, v59
	v_sub_f32_e32 v59, v61, v82
	v_exp_f32_e32 v61, v59
	v_cndmask_b32_e32 v58, 0, v93, vcc
	v_cmp_lt_i32_e32 vcc, 3, v83
	s_nop 1
	v_cndmask_b32_e32 v59, 0, v92, vcc
	v_add_f32_e32 v92, 0, v59
	v_add_f32_e32 v94, v58, v92
	v_pk_mul_f32 v[92:93], v[68:69], v[60:61]
	v_cmp_lt_i32_e32 vcc, 6, v83
	s_nop 1
	v_cndmask_b32_e32 v60, 0, v93, vcc
	v_cmp_lt_i32_e32 vcc, 5, v83
	s_nop 1
	v_cndmask_b32_e32 v61, 0, v92, vcc
	v_add_f32_e32 v92, v61, v94
	v_add_f32_e32 v92, v60, v92
	s_nop 1
	v_add_f32_dpp v92, v92, v92 quad_perm:[1,0,3,2] row_mask:0xf bank_mask:0xf bound_ctrl:1
	s_nop 1
	v_mov_b32_dpp v93, v92 quad_perm:[2,3,0,1] row_mask:0xf bank_mask:0xf bound_ctrl:1
	s_and_saveexec_b64 s[6:7], s[30:31]
	v_add_f32_e32 v92, v92, v93
	ds_write_b32 v0, v92 offset:4100
	s_or_b64 exec, exec, s[6:7]
	v_sub_f32_e32 v54, v54, v82
	v_sub_f32_e32 v55, v55, v82
	v_exp_f32_e32 v54, v54
	v_exp_f32_e32 v55, v55
	v_cmp_lt_i32_e32 vcc, 32, v83
	v_pk_mul_f32 v[92:93], v[68:69], v[54:55]
	v_sub_f32_e32 v55, v56, v82
	v_exp_f32_e32 v56, v55
	v_sub_f32_e32 v55, v57, v82
	v_exp_f32_e32 v57, v55
	v_cndmask_b32_e32 v54, 0, v93, vcc
	v_cmp_lt_i32_e32 vcc, 31, v83
	s_nop 1
	v_cndmask_b32_e32 v55, 0, v92, vcc
	v_add_f32_e32 v92, 0, v55
	v_add_f32_e32 v94, v54, v92
	v_pk_mul_f32 v[92:93], v[68:69], v[56:57]
	v_cmp_lt_i32_e32 vcc, 34, v83
	s_nop 1
	v_cndmask_b32_e32 v56, 0, v93, vcc
	v_cmp_lt_i32_e32 vcc, 33, v83
	s_nop 1
	v_cndmask_b32_e32 v57, 0, v92, vcc
	v_add_f32_e32 v92, v57, v94
	v_add_f32_e32 v92, v56, v92
	s_nop 1
	v_add_f32_dpp v92, v92, v92 quad_perm:[1,0,3,2] row_mask:0xf bank_mask:0xf bound_ctrl:1
	s_nop 1
	v_mov_b32_dpp v93, v92 quad_perm:[2,3,0,1] row_mask:0xf bank_mask:0xf bound_ctrl:1
	s_and_saveexec_b64 s[6:7], s[30:31]
	v_add_f32_e32 v92, v92, v93
	ds_write_b32 v0, v92 offset:4128
	s_or_b64 exec, exec, s[6:7]
	v_sub_f32_e32 v50, v50, v82
	v_sub_f32_e32 v51, v51, v82
	v_exp_f32_e32 v50, v50
	v_exp_f32_e32 v51, v51
	v_cmp_lt_i32_e32 vcc, 36, v83
	v_pk_mul_f32 v[92:93], v[68:69], v[50:51]
	v_sub_f32_e32 v51, v52, v82
	v_exp_f32_e32 v52, v51
	v_sub_f32_e32 v51, v53, v82
	v_exp_f32_e32 v53, v51
	v_cndmask_b32_e32 v50, 0, v93, vcc
	v_cmp_lt_i32_e32 vcc, 35, v83
	s_nop 1
	v_cndmask_b32_e32 v51, 0, v92, vcc
	v_add_f32_e32 v92, 0, v51
	v_add_f32_e32 v94, v50, v92
	v_pk_mul_f32 v[92:93], v[68:69], v[52:53]
	v_cmp_lt_i32_e32 vcc, 38, v83
	s_nop 1
	v_cndmask_b32_e32 v52, 0, v93, vcc
	v_cmp_lt_i32_e32 vcc, 37, v83
	s_nop 1
	v_cndmask_b32_e32 v53, 0, v92, vcc
	v_add_f32_e32 v92, v53, v94
	v_add_f32_e32 v92, v52, v92
	s_nop 1
	v_add_f32_dpp v92, v92, v92 quad_perm:[1,0,3,2] row_mask:0xf bank_mask:0xf bound_ctrl:1
	s_nop 1
	v_mov_b32_dpp v93, v92 quad_perm:[2,3,0,1] row_mask:0xf bank_mask:0xf bound_ctrl:1
	s_and_saveexec_b64 s[6:7], s[30:31]
	s_cbranch_execz .LBB0_1071
	v_add_f32_e32 v92, v92, v93
	ds_write_b32 v0, v92 offset:4132
	s_branch .LBB0_1071
